# attention: waves 4-7 take the per-pair workgroup barrier one phase earlier (stagger: the two waves of a SIMD run complementary QK/exp and PV/max phases), both layers
# speedup vs baseline: 1.0009x; 1.0009x over previous
; #define LAS __attribute__((address_space(3)))
; __device__ __forceinline__ void att_qk_exp(const LAS char* kb, const bf16x8 (&qf)[6], float nm, fa::f32x16& n0, fa::f32x16& n1, fa::f32x16& p0, fa::f32x16& p1, float& lsum, bf16x8 (&pf)[4]) {
;     const fa::f32x16 zero = {0.f, 0.f, 0.f, 0.f, 0.f, 0.f, 0.f, 0.f, 0.f, 0.f, 0.f, 0.f, 0.f, 0.f, 0.f, 0.f};
;     bf16x8 kc0 = *(const LAS bf16x8*)kb, kc1 = *(const LAS bf16x8*)(kb + 32 * fa::KP_A);
;     float ps = 0.f, ps2 = 0.f;
; #pragma unroll
;     for (int st = 0; st < 6; ++st) {
;         bf16x8 kn0 = kc0, kn1 = kc1;
;         if (st < 5) { kn0 = *(const LAS bf16x8*)(kb + 32 * (st + 1)); kn1 = *(const LAS bf16x8*)(kb + 32 * fa::KP_A + 32 * (st + 1)); }
;         n0 = __builtin_amdgcn_mfma_f32_32x32x16_bf16(kc0, qf[st], st == 0 ? zero : n0, 0, 0, 0);
;         n1 = __builtin_amdgcn_mfma_f32_32x32x16_bf16(kc1, qf[st], st == 0 ? zero : n1, 0, 0, 0);
;         constexpr int lo[7] = {0, 2, 6, 8, 10, 14, 16};
; #pragma unroll
;         for (int r = lo[st]; r < lo[st + 1]; ++r) {
;             p0[r] = __builtin_amdgcn_exp2f(vadd1(p0[r], nm)); p1[r] = __builtin_amdgcn_exp2f(vadd1(p1[r], nm));
;             ps += p0[r]; ps += p1[r]; }
;         kc0 = kn0; kc1 = kn1;
;         __builtin_amdgcn_sched_barrier(0);
;     }
;     lsum += ps + ps2;
;     pf[0] = fa::pack_p(p0, 0); pf[1] = fa::pack_p(p0, 8); pf[2] = fa::pack_p(p1, 0); pf[3] = fa::pack_p(p1, 8);
; }
; __device__ __forceinline__ float att_pv_max(fa::f32x16& o0, fa::f32x16& o1, const LAS char* vb, const bf16x8 (&pf)[4], const fa::f32x16& n0, const fa::f32x16& n1) {
;     using namespace fa;
;     float ta = n0[0], tb = n1[0];
;     s16x4 a0 = vtr(vb), a1 = vtr(vb + 512), b0 = vtr(vb + 4096), b1 = vtr(vb + 4096 + 512);
; #pragma unroll
;     for (int ks = 0; ks < 4; ++ks) {
;         s16x4 na0 = a0, na1 = a1, nb0 = b0, nb1 = b1;
;         if (ks < 3) { na0 = vtr(vb + (ks + 1) * 1024); na1 = vtr(vb + (ks + 1) * 1024 + 512); nb0 = vtr(vb + 4096 + (ks + 1) * 1024); nb1 = vtr(vb + 4096 + (ks + 1) * 1024 + 512); }
;         const bf16x8 v0 = (bf16x8){a0[0], a0[1], a0[2], a0[3], a1[0], a1[1], a1[2], a1[3]}, v1 = (bf16x8){b0[0], b0[1], b0[2], b0[3], b1[0], b1[1], b1[2], b1[3]};
;         o0 = __builtin_amdgcn_mfma_f32_32x32x16_bf16(v0, pf[ks], o0, 0, 0, 0);
;         o1 = __builtin_amdgcn_mfma_f32_32x32x16_bf16(v1, pf[ks], o1, 0, 0, 0);
.LBB0_1031:
	s_add_i32 s8, s8, 0
	v_add3_u32 v67, s8, v187, v180
	ds_read_b128 v[34:37], v67 offset:21504
	ds_read_b128 v[50:53], v67 offset:28160
	ds_read_b128 v[68:71], v67 offset:21536
	s_waitcnt lgkmcnt(1)
	v_mfma_f32_32x32x16_bf16 v[50:65], v[50:53], v[132:135], v[226:241]
	ds_read_b128 v[72:75], v67 offset:28192
	v_exp_f32_e32 v2, v2
	v_exp_f32_e32 v18, v18
	v_exp_f32_e32 v3, v3
	v_mfma_f32_32x32x16_bf16 v[34:49], v[34:37], v[132:135], v[226:241]
	v_exp_f32_e32 v19, v19
	s_waitcnt lgkmcnt(1)
	v_mfma_f32_32x32x16_bf16 v[34:49], v[68:71], v[136:139], v[34:49]
	ds_read_b128 v[76:79], v67 offset:21568
	ds_read_b128 v[80:83], v67 offset:28224
	s_waitcnt lgkmcnt(2)
	v_mfma_f32_32x32x16_bf16 v[50:65], v[72:75], v[136:139], v[50:65]
	v_exp_f32_e32 v4, v4
	v_exp_f32_e32 v20, v20
	v_exp_f32_e32 v5, v5
	v_exp_f32_e32 v21, v21
	v_exp_f32_e32 v6, v6
	v_exp_f32_e32 v22, v22
	v_exp_f32_e32 v7, v7
	v_exp_f32_e32 v23, v23
	s_waitcnt lgkmcnt(1)
	v_mfma_f32_32x32x16_bf16 v[34:49], v[76:79], v[140:143], v[34:49]
	ds_read_b128 v[68:71], v67 offset:21600
	ds_read_b128 v[72:75], v67 offset:28256
	s_nop 0
	v_exp_f32_e32 v8, v8
	s_waitcnt lgkmcnt(2)
	v_mfma_f32_32x32x16_bf16 v[50:65], v[80:83], v[140:143], v[50:65]
	v_exp_f32_e32 v24, v24
	v_exp_f32_e32 v9, v9
	v_exp_f32_e32 v25, v25
	s_waitcnt lgkmcnt(1)
	v_mfma_f32_32x32x16_bf16 v[34:49], v[68:71], v[144:147], v[34:49]
	ds_read_b128 v[76:79], v67 offset:21632
	ds_read_b128 v[80:83], v67 offset:28288
	s_nop 0
	v_exp_f32_e32 v10, v10
	s_waitcnt lgkmcnt(2)
	v_mfma_f32_32x32x16_bf16 v[50:65], v[72:75], v[144:147], v[50:65]
	v_exp_f32_e32 v26, v26
	v_exp_f32_e32 v11, v11
	v_exp_f32_e32 v27, v27
	s_waitcnt lgkmcnt(1)
	v_mfma_f32_32x32x16_bf16 v[34:49], v[76:79], v[148:151], v[34:49]
	ds_read_b128 v[68:71], v67 offset:21664
	ds_read_b128 v[72:75], v67 offset:28320
	s_waitcnt lgkmcnt(2)
	v_mfma_f32_32x32x16_bf16 v[50:65], v[80:83], v[148:151], v[50:65]
	v_exp_f32_e32 v12, v12
	v_exp_f32_e32 v28, v28
	v_exp_f32_e32 v13, v13
	v_exp_f32_e32 v29, v29
	v_exp_f32_e32 v14, v14
	v_exp_f32_e32 v30, v30
	v_exp_f32_e32 v15, v15
	v_exp_f32_e32 v31, v31
	v_add_f32_e32 v67, 0, v2
	v_add_f32_e32 v67, v18, v67
	v_add_f32_e32 v67, v67, v3
	v_add_f32_e32 v67, v19, v67
	v_add_f32_e32 v67, v67, v4
	v_add_f32_e32 v67, v20, v67
	v_add_f32_e32 v67, v67, v5
	v_add_f32_e32 v67, v21, v67
	v_add_f32_e32 v67, v67, v6
	v_add_f32_e32 v67, v22, v67
	v_add_f32_e32 v67, v67, v7
	v_add_f32_e32 v67, v23, v67
	v_add_f32_e32 v67, v67, v8
	v_add_f32_e32 v67, v24, v67
	v_add_f32_e32 v67, v67, v9
	v_add_f32_e32 v67, v25, v67
	v_add_f32_e32 v67, v67, v10
	v_add_f32_e32 v67, v26, v67
	v_add_f32_e32 v67, v67, v11
	v_add_f32_e32 v67, v27, v67
	v_add_f32_e32 v67, v67, v12
	v_add_f32_e32 v67, v28, v67
	v_add_f32_e32 v67, v67, v13
	v_add_f32_e32 v67, v29, v67
	v_exp_f32_e32 v16, v16
	s_waitcnt lgkmcnt(1)
	v_mfma_f32_32x32x16_bf16 v[34:49], v[68:71], v[152:155], v[34:49]
	v_add_f32_e32 v67, v67, v14
	v_exp_f32_e32 v32, v32
	v_add_f32_e32 v67, v30, v67
	v_exp_f32_e32 v17, v17
	v_add_f32_e32 v67, v67, v15
	s_waitcnt lgkmcnt(0)
	v_mfma_f32_32x32x16_bf16 v[50:65], v[72:75], v[152:155], v[50:65]
	v_exp_f32_e32 v33, v33
	v_add_f32_e32 v67, v31, v67
	v_add_f32_e32 v67, v67, v16
	v_add_f32_e32 v67, v32, v67
	v_add_f32_e32 v67, v67, v17
	v_add_f32_e32 v67, v33, v67
	v_add_u32_e32 v193, s8, v189
	v_cvt_pk_bf16_f32 v68, v2, v3
	v_cvt_pk_bf16_f32 v69, v4, v5
	v_cvt_pk_bf16_f32 v70, v6, v7
	v_cvt_pk_bf16_f32 v71, v8, v9
	v_cvt_pk_bf16_f32 v72, v10, v11
	v_cvt_pk_bf16_f32 v73, v12, v13
	v_cvt_pk_bf16_f32 v74, v14, v15
	v_cvt_pk_bf16_f32 v75, v16, v17
	v_cvt_pk_bf16_f32 v76, v18, v19
	v_cvt_pk_bf16_f32 v77, v20, v21
	v_cvt_pk_bf16_f32 v78, v22, v23
	v_cvt_pk_bf16_f32 v79, v24, v25
	v_cvt_pk_bf16_f32 v196, v26, v27
	v_cvt_pk_bf16_f32 v197, v28, v29
	v_cvt_pk_bf16_f32 v198, v30, v31
	v_cvt_pk_bf16_f32 v199, v32, v33
	s_cmp_eq_u64 s[4:5], 0
	s_cbranch_scc0 .Lstg_x_L0
	s_barrier
.Lstg_x_L0:
	ds_read_b64_tr_b16 v[80:81], v193 offset:13312
	ds_read_b64_tr_b16 v[82:83], v193 offset:13824
	ds_read_b64_tr_b16 v[84:85], v193 offset:14336
	ds_read_b64_tr_b16 v[86:87], v193 offset:14848
	s_waitcnt lgkmcnt(2)
	v_mfma_f32_32x32x16_bf16 v[114:129], v[80:83], v[68:71], v[114:129]
	ds_read_b64_tr_b16 v[80:81], v193 offset:17408
	ds_read_b64_tr_b16 v[82:83], v193 offset:17920
	ds_read_b64_tr_b16 v[88:89], v193 offset:18432
	ds_read_b64_tr_b16 v[90:91], v193 offset:18944
	v_add_f32_e32 v67, 0, v67
	v_add_f32_e32 v192, v66, v67
	s_waitcnt lgkmcnt(2)
	v_mfma_f32_32x32x16_bf16 v[98:113], v[80:83], v[68:71], v[98:113]
	s_waitcnt lgkmcnt(0)
	v_mfma_f32_32x32x16_bf16 v[98:113], v[88:91], v[72:75], v[98:113]
	ds_read_b64_tr_b16 v[66:67], v193 offset:15360
	ds_read_b64_tr_b16 v[68:69], v193 offset:15872
	ds_read_b64_tr_b16 v[80:81], v193 offset:19456
	ds_read_b64_tr_b16 v[82:83], v193 offset:19968
	v_mfma_f32_32x32x16_bf16 v[114:129], v[84:87], v[72:75], v[114:129]
	s_waitcnt lgkmcnt(0)
	v_mfma_f32_32x32x16_bf16 v[98:113], v[80:83], v[76:79], v[98:113]
	ds_read_b64_tr_b16 v[84:85], v193 offset:16384
	ds_read_b64_tr_b16 v[86:87], v193 offset:16896
	ds_read_b64_tr_b16 v[200:201], v193 offset:20480
	ds_read_b64_tr_b16 v[202:203], v193 offset:20992
	v_mfma_f32_32x32x16_bf16 v[114:129], v[66:69], v[76:79], v[114:129]
	v_max_f32_e32 v66, v51, v51
	v_max_f32_e32 v67, v50, v50
	v_max_f32_e32 v66, v67, v66
	v_max3_f32 v66, v66, v52, v53
	v_max3_f32 v66, v66, v54, v55
	v_max3_f32 v66, v66, v56, v57
	v_max3_f32 v82, v66, v58, v59
	v_max3_f32 v66, v82, v60, v61
	v_max3_f32 v82, v34, v35, v36
	v_max3_f32 v82, v82, v37, v38
	v_max3_f32 v82, v82, v39, v40
	v_max3_f32 v82, v82, v41, v42
	s_waitcnt lgkmcnt(2)
	v_mfma_f32_32x32x16_bf16 v[114:129], v[84:87], v[196:199], v[114:129]
	v_max3_f32 v67, v82, v43, v44
	v_max3_f32 v82, v67, v45, v46
	v_max3_f32 v83, v66, v62, v63
	s_waitcnt lgkmcnt(0)
	v_mfma_f32_32x32x16_bf16 v[98:113], v[200:203], v[196:199], v[98:113]
	v_max3_f32 v82, v82, v47, v48
	v_max3_f32 v83, v83, v64, v65
	v_max3_f32 v82, v82, v49, v83
	v_cmp_lt_f32_e32 vcc, 0x41000000, v82
	s_cbranch_vccz .LBB0_1033
; __device__ __forceinline__ void att_shift(float tm, bool first, float& mrun, float& lsum, fa::f32x16& o0, fa::f32x16& o1) {
;     if (first || __any(tm > mrun + 8.f)) {
;         tm = fmaxf(tm, __shfl_xor(tm, 32));
;         const float dl = first ? 0.f : fmaxf(tm - mrun, 0.f), alpha = __builtin_amdgcn_exp2f(-dl);
;         mrun = first ? tm : mrun + dl; lsum *= alpha;
; #pragma unroll
;         for (int r = 0; r < 16; ++r) { o0[r] *= alpha; o1[r] *= alpha; }
;     }
; }
; __device__ __forceinline__ void ph_attn_mfma(unsigned char* lds_, const bf16_t* Q, const bf16_t* Kb, const bf16_t* Vb, bf16_t* Z, int with_ctx, int u0, int ustep) { PH_IDS;
;     ...
;             att_shift(tmB, false, mrun, lsum, o0, o1);
;             __syncthreads();
;             if (more) {
;                 att_qk_exp(sm + nxt + r32 * KP_A + 16 * hi, qf, -mrun, a0, a1, b0, b1, lsum, pf);
;                 tmA = att_pv_max(o0, o1, sm + cur + BUF_A + vrd, pf, a0, a1);
;             } else {
;                 att_exp_pack(b0, b1, -mrun, lsum, pf);
;                 pv_tile(o0, o1, sm + cur + BUF_A + vrd, pf);
	v_and_b32_e32 v84, 64, v1
	v_xor_b32_e32 v83, 32, v1
	v_add_u32_e32 v84, 64, v84
	v_cmp_lt_i32_e32 vcc, v83, v84
	s_nop 1
	v_cndmask_b32_e32 v83, v1, v83, vcc
	v_lshlrev_b32_e32 v83, 2, v83
	ds_bpermute_b32 v83, v83, v82
	v_max_f32_e32 v82, v82, v82
	s_waitcnt lgkmcnt(0)
	v_max_f32_e32 v83, v83, v83
	v_max_f32_e32 v82, v82, v83
	v_max_f32_e32 v83, 0, v82
	v_exp_f32_e64 v82, -v83
	v_add_f32_e32 v190, v190, v83
	v_mul_f32_e32 v192, v192, v82
	v_pk_mul_f32 v[128:129], v[128:129], v[82:83] op_sel_hi:[1,0]
	v_pk_mul_f32 v[126:127], v[126:127], v[82:83] op_sel_hi:[1,0]
	v_pk_mul_f32 v[124:125], v[124:125], v[82:83] op_sel_hi:[1,0]
	v_pk_mul_f32 v[122:123], v[122:123], v[82:83] op_sel_hi:[1,0]
	v_pk_mul_f32 v[120:121], v[120:121], v[82:83] op_sel_hi:[1,0]
	v_pk_mul_f32 v[118:119], v[118:119], v[82:83] op_sel_hi:[1,0]
	v_pk_mul_f32 v[116:117], v[116:117], v[82:83] op_sel_hi:[1,0]
	v_pk_mul_f32 v[114:115], v[114:115], v[82:83] op_sel_hi:[1,0]
	v_pk_mul_f32 v[112:113], v[112:113], v[82:83] op_sel_hi:[1,0]
	v_pk_mul_f32 v[110:111], v[110:111], v[82:83] op_sel_hi:[1,0]
	v_pk_mul_f32 v[108:109], v[108:109], v[82:83] op_sel_hi:[1,0]
	v_pk_mul_f32 v[106:107], v[106:107], v[82:83] op_sel_hi:[1,0]
	v_pk_mul_f32 v[104:105], v[104:105], v[82:83] op_sel_hi:[1,0]
	v_pk_mul_f32 v[102:103], v[102:103], v[82:83] op_sel_hi:[1,0]
	v_pk_mul_f32 v[100:101], v[100:101], v[82:83] op_sel_hi:[1,0]
	v_pk_mul_f32 v[98:99], v[98:99], v[82:83] op_sel_hi:[1,0]
	v_sub_f32_e32 v34, v34, v83
	v_sub_f32_e32 v35, v35, v83
	v_sub_f32_e32 v36, v36, v83
	v_sub_f32_e32 v37, v37, v83
	v_sub_f32_e32 v38, v38, v83
	v_sub_f32_e32 v39, v39, v83
	v_sub_f32_e32 v40, v40, v83
	v_sub_f32_e32 v41, v41, v83
	v_sub_f32_e32 v42, v42, v83
	v_sub_f32_e32 v43, v43, v83
	v_sub_f32_e32 v44, v44, v83
	v_sub_f32_e32 v45, v45, v83
	v_sub_f32_e32 v46, v46, v83
	v_sub_f32_e32 v47, v47, v83
	v_sub_f32_e32 v48, v48, v83
	v_sub_f32_e32 v49, v49, v83
	v_sub_f32_e32 v50, v50, v83
	v_sub_f32_e32 v51, v51, v83
	v_sub_f32_e32 v52, v52, v83
	v_sub_f32_e32 v53, v53, v83
	v_sub_f32_e32 v54, v54, v83
	v_sub_f32_e32 v55, v55, v83
	v_sub_f32_e32 v56, v56, v83
	v_sub_f32_e32 v57, v57, v83
	v_sub_f32_e32 v58, v58, v83
	v_sub_f32_e32 v59, v59, v83
	v_sub_f32_e32 v60, v60, v83
	v_sub_f32_e32 v61, v61, v83
	v_sub_f32_e32 v62, v62, v83
	v_sub_f32_e32 v63, v63, v83
	v_sub_f32_e32 v64, v64, v83
	v_sub_f32_e32 v65, v65, v83
	v_sub_f32_e32 v226, v226, v83
	v_sub_f32_e32 v227, v227, v83
	v_sub_f32_e32 v228, v228, v83
	v_sub_f32_e32 v229, v229, v83
	v_sub_f32_e32 v230, v230, v83
	v_sub_f32_e32 v231, v231, v83
	v_sub_f32_e32 v232, v232, v83
	v_sub_f32_e32 v233, v233, v83
	v_sub_f32_e32 v234, v234, v83
	v_sub_f32_e32 v235, v235, v83
	v_sub_f32_e32 v236, v236, v83
	v_sub_f32_e32 v237, v237, v83
	v_sub_f32_e32 v238, v238, v83
	v_sub_f32_e32 v239, v239, v83
	v_sub_f32_e32 v240, v240, v83
	v_sub_f32_e32 v241, v241, v83
.LBB0_1033:
	s_mov_b64 s[8:9], -1
	s_and_b64 vcc, exec, s[10:11]
	v_xor_b32_e32 v194, 0x80000000, v190
	s_cmp_eq_u64 s[4:5], 0
	s_cbranch_scc1 .Lstg_y_L0
	s_barrier
.Lstg_y_L0:
	s_cbranch_vccz .LBB0_1035
	s_nop 0
	v_exp_f32_e32 v82, v34
	v_exp_f32_e32 v83, v50
	v_exp_f32_e32 v85, v35
	v_exp_f32_e32 v86, v51
	v_add_f32_e32 v84, 0, v82
	v_exp_f32_e32 v87, v36
	v_add_f32_e32 v84, v83, v84
	v_exp_f32_e32 v88, v52
	v_add_f32_e32 v84, v84, v85
	v_exp_f32_e32 v89, v37
	v_add_f32_e32 v84, v86, v84
	v_exp_f32_e32 v90, v53
	v_add_f32_e32 v84, v84, v87
	v_exp_f32_e32 v91, v38
	v_add_f32_e32 v84, v88, v84
	v_exp_f32_e32 v92, v54
	v_add_f32_e32 v84, v84, v89
	v_exp_f32_e32 v93, v39
	v_add_f32_e32 v84, v90, v84
	v_exp_f32_e32 v94, v55
	v_add_f32_e32 v84, v84, v91
	v_exp_f32_e32 v95, v40
	v_add_f32_e32 v84, v92, v84
	v_exp_f32_e32 v96, v56
	v_add_f32_e32 v84, v84, v93
	v_exp_f32_e32 v97, v41
	v_add_f32_e32 v84, v94, v84
	v_exp_f32_e32 v66, v57
	v_add_f32_e32 v84, v84, v95
	v_exp_f32_e32 v67, v42
	v_add_f32_e32 v84, v96, v84
	v_exp_f32_e32 v68, v58
	v_add_f32_e32 v84, v84, v97
	v_exp_f32_e32 v69, v43
	v_add_f32_e32 v84, v66, v84
	v_exp_f32_e32 v70, v59
	v_add_f32_e32 v84, v84, v67
	v_exp_f32_e32 v71, v44
	v_add_f32_e32 v84, v68, v84
	v_exp_f32_e32 v72, v60
	v_add_f32_e32 v84, v84, v69
	v_exp_f32_e32 v73, v45
	v_add_f32_e32 v84, v70, v84
	v_exp_f32_e32 v74, v61
	v_add_f32_e32 v84, v84, v71
	v_exp_f32_e32 v75, v46
	v_add_f32_e32 v84, v72, v84
	v_exp_f32_e32 v76, v62
	v_add_f32_e32 v84, v84, v73
	v_exp_f32_e32 v77, v47
	v_add_f32_e32 v84, v74, v84
	v_exp_f32_e32 v78, v63
	v_add_f32_e32 v84, v84, v75
	v_exp_f32_e32 v79, v48
	v_add_f32_e32 v84, v76, v84
	v_exp_f32_e32 v80, v64
	v_add_f32_e32 v84, v84, v77
	v_exp_f32_e32 v81, v49
	v_add_f32_e32 v84, v78, v84
	v_add_f32_e32 v84, v84, v79
	v_exp_f32_e32 v204, v65
	v_add_f32_e32 v84, v80, v84
	v_add_f32_e32 v84, v84, v81
	v_cvt_pk_bf16_f32 v196, v82, v85
	v_add_f32_e32 v195, v204, v84
	v_cvt_pk_bf16_f32 v197, v87, v89
	v_cvt_pk_bf16_f32 v198, v91, v93
	v_cvt_pk_bf16_f32 v199, v95, v97
	v_cvt_pk_bf16_f32 v200, v67, v69
	v_cvt_pk_bf16_f32 v201, v71, v73
	v_cvt_pk_bf16_f32 v202, v75, v77
	v_cvt_pk_bf16_f32 v203, v79, v81
	v_cvt_pk_bf16_f32 v214, v83, v86
	v_cvt_pk_bf16_f32 v215, v88, v90
	v_cvt_pk_bf16_f32 v216, v92, v94
	v_cvt_pk_bf16_f32 v217, v96, v66
	v_cvt_pk_bf16_f32 v218, v68, v70
	v_cvt_pk_bf16_f32 v219, v72, v74
	v_cvt_pk_bf16_f32 v220, v76, v78
	v_cvt_pk_bf16_f32 v221, v80, v204
	ds_read_b64_tr_b16 v[82:83], v193 offset:34816
	ds_read_b64_tr_b16 v[84:85], v193 offset:35328
	ds_read_b64_tr_b16 v[222:223], v193 offset:38912
	ds_read_b64_tr_b16 v[224:225], v193 offset:39424
	s_waitcnt lgkmcnt(2)
	v_mfma_f32_32x32x16_bf16 v[114:129], v[82:85], v[196:199], v[114:129]
	s_mov_b64 s[8:9], 0
	s_waitcnt lgkmcnt(0)
	v_mfma_f32_32x32x16_bf16 v[98:113], v[222:225], v[196:199], v[98:113]
	ds_read_b64_tr_b16 v[196:197], v193 offset:35840
	ds_read_b64_tr_b16 v[198:199], v193 offset:36352
	ds_read_b64_tr_b16 v[222:223], v193 offset:39936
	ds_read_b64_tr_b16 v[224:225], v193 offset:40448
	s_waitcnt lgkmcnt(2)
	v_mfma_f32_32x32x16_bf16 v[114:129], v[196:199], v[200:203], v[114:129]
	s_waitcnt lgkmcnt(0)
	v_mfma_f32_32x32x16_bf16 v[98:113], v[222:225], v[200:203], v[98:113]
	ds_read_b64_tr_b16 v[196:197], v193 offset:36864
	ds_read_b64_tr_b16 v[198:199], v193 offset:37376
	ds_read_b64_tr_b16 v[200:201], v193 offset:40960
	ds_read_b64_tr_b16 v[202:203], v193 offset:41472
	s_waitcnt lgkmcnt(2)
	v_mfma_f32_32x32x16_bf16 v[114:129], v[196:199], v[214:217], v[114:129]
	s_waitcnt lgkmcnt(0)
	v_mfma_f32_32x32x16_bf16 v[98:113], v[200:203], v[214:217], v[98:113]
	ds_read_b64_tr_b16 v[196:197], v193 offset:37888
	ds_read_b64_tr_b16 v[198:199], v193 offset:38400
	ds_read_b64_tr_b16 v[200:201], v193 offset:41984
	ds_read_b64_tr_b16 v[202:203], v193 offset:42496
	s_waitcnt lgkmcnt(2)
	v_mfma_f32_32x32x16_bf16 v[114:129], v[196:199], v[218:221], v[114:129]
	s_waitcnt lgkmcnt(0)
	v_mfma_f32_32x32x16_bf16 v[98:113], v[200:203], v[218:221], v[98:113]

; #define LAS __attribute__((address_space(3)))
; __device__ __forceinline__ void att_qk_exp(const LAS char* kb, const bf16x8 (&qf)[6], float nm, fa::f32x16& n0, fa::f32x16& n1, fa::f32x16& p0, fa::f32x16& p1, float& lsum, bf16x8 (&pf)[4]) {
;     const fa::f32x16 zero = {0.f, 0.f, 0.f, 0.f, 0.f, 0.f, 0.f, 0.f, 0.f, 0.f, 0.f, 0.f, 0.f, 0.f, 0.f, 0.f};
;     bf16x8 kc0 = *(const LAS bf16x8*)kb, kc1 = *(const LAS bf16x8*)(kb + 32 * fa::KP_A);
;     float ps = 0.f, ps2 = 0.f;
; #pragma unroll
;     for (int st = 0; st < 6; ++st) {
;         bf16x8 kn0 = kc0, kn1 = kc1;
;         if (st < 5) { kn0 = *(const LAS bf16x8*)(kb + 32 * (st + 1)); kn1 = *(const LAS bf16x8*)(kb + 32 * fa::KP_A + 32 * (st + 1)); }
;         n0 = __builtin_amdgcn_mfma_f32_32x32x16_bf16(kc0, qf[st], st == 0 ? zero : n0, 0, 0, 0);
;         n1 = __builtin_amdgcn_mfma_f32_32x32x16_bf16(kc1, qf[st], st == 0 ? zero : n1, 0, 0, 0);
;         constexpr int lo[7] = {0, 2, 6, 8, 10, 14, 16};
; #pragma unroll
;         for (int r = lo[st]; r < lo[st + 1]; ++r) {
;             p0[r] = __builtin_amdgcn_exp2f(vadd1(p0[r], nm)); p1[r] = __builtin_amdgcn_exp2f(vadd1(p1[r], nm));
;             ps += p0[r]; ps += p1[r]; }
;         kc0 = kn0; kc1 = kn1;
;         __builtin_amdgcn_sched_barrier(0);
;     }
;     lsum += ps + ps2;
;     pf[0] = fa::pack_p(p0, 0); pf[1] = fa::pack_p(p0, 8); pf[2] = fa::pack_p(p1, 0); pf[3] = fa::pack_p(p1, 8);
; }
; __device__ __forceinline__ float att_pv_max(fa::f32x16& o0, fa::f32x16& o1, const LAS char* vb, const bf16x8 (&pf)[4], const fa::f32x16& n0, const fa::f32x16& n1) {
;     using namespace fa;
;     float ta = n0[0], tb = n1[0];
;     s16x4 a0 = vtr(vb), a1 = vtr(vb + 512), b0 = vtr(vb + 4096), b1 = vtr(vb + 4096 + 512);
; #pragma unroll
;     for (int ks = 0; ks < 4; ++ks) {
;         s16x4 na0 = a0, na1 = a1, nb0 = b0, nb1 = b1;
;         if (ks < 3) { na0 = vtr(vb + (ks + 1) * 1024); na1 = vtr(vb + (ks + 1) * 1024 + 512); nb0 = vtr(vb + 4096 + (ks + 1) * 1024); nb1 = vtr(vb + 4096 + (ks + 1) * 1024 + 512); }
;         const bf16x8 v0 = (bf16x8){a0[0], a0[1], a0[2], a0[3], a1[0], a1[1], a1[2], a1[3]}, v1 = (bf16x8){b0[0], b0[1], b0[2], b0[3], b1[0], b1[1], b1[2], b1[3]};
;         o0 = __builtin_amdgcn_mfma_f32_32x32x16_bf16(v0, pf[ks], o0, 0, 0, 0);
;         o1 = __builtin_amdgcn_mfma_f32_32x32x16_bf16(v1, pf[ks], o1, 0, 0, 0);
.LBB0_2991:
	s_add_i32 s8, s8, 0
	v_add3_u32 v99, s8, v217, v188
	ds_read_b128 v[34:37], v99 offset:21504
	ds_read_b128 v[50:53], v99 offset:28160
	ds_read_b128 v[100:103], v99 offset:21536
	s_waitcnt lgkmcnt(1)
	v_mfma_f32_32x32x16_bf16 v[50:65], v[50:53], v[134:137], v[232:247]
	ds_read_b128 v[104:107], v99 offset:28192
	v_exp_f32_e32 v2, v2
	v_exp_f32_e32 v18, v18
	v_exp_f32_e32 v3, v3
	v_mfma_f32_32x32x16_bf16 v[34:49], v[34:37], v[134:137], v[232:247]
	v_exp_f32_e32 v19, v19
	s_waitcnt lgkmcnt(1)
	v_mfma_f32_32x32x16_bf16 v[34:49], v[100:103], v[138:141], v[34:49]
	ds_read_b128 v[108:111], v99 offset:21568
	ds_read_b128 v[112:115], v99 offset:28224
	s_waitcnt lgkmcnt(2)
	v_mfma_f32_32x32x16_bf16 v[50:65], v[104:107], v[138:141], v[50:65]
	v_exp_f32_e32 v4, v4
	v_exp_f32_e32 v20, v20
	v_exp_f32_e32 v5, v5
	v_exp_f32_e32 v21, v21
	v_exp_f32_e32 v6, v6
	v_exp_f32_e32 v22, v22
	v_exp_f32_e32 v7, v7
	v_exp_f32_e32 v23, v23
	s_waitcnt lgkmcnt(1)
	v_mfma_f32_32x32x16_bf16 v[34:49], v[108:111], v[142:145], v[34:49]
	ds_read_b128 v[100:103], v99 offset:21600
	ds_read_b128 v[104:107], v99 offset:28256
	s_nop 0
	v_exp_f32_e32 v8, v8
	s_waitcnt lgkmcnt(2)
	v_mfma_f32_32x32x16_bf16 v[50:65], v[112:115], v[142:145], v[50:65]
	v_exp_f32_e32 v24, v24
	v_exp_f32_e32 v9, v9
	v_exp_f32_e32 v25, v25
	s_waitcnt lgkmcnt(1)
	v_mfma_f32_32x32x16_bf16 v[34:49], v[100:103], v[146:149], v[34:49]
	ds_read_b128 v[108:111], v99 offset:21632
	ds_read_b128 v[112:115], v99 offset:28288
	s_nop 0
	v_exp_f32_e32 v10, v10
	s_waitcnt lgkmcnt(2)
	v_mfma_f32_32x32x16_bf16 v[50:65], v[104:107], v[146:149], v[50:65]
	v_exp_f32_e32 v26, v26
	v_exp_f32_e32 v11, v11
	v_exp_f32_e32 v27, v27
	s_waitcnt lgkmcnt(1)
	v_mfma_f32_32x32x16_bf16 v[34:49], v[108:111], v[150:153], v[34:49]
	ds_read_b128 v[100:103], v99 offset:21664
	ds_read_b128 v[104:107], v99 offset:28320
	s_waitcnt lgkmcnt(2)
	v_mfma_f32_32x32x16_bf16 v[50:65], v[112:115], v[150:153], v[50:65]
	v_exp_f32_e32 v12, v12
	v_exp_f32_e32 v28, v28
	v_exp_f32_e32 v13, v13
	v_exp_f32_e32 v29, v29
	v_exp_f32_e32 v14, v14
	v_exp_f32_e32 v30, v30
	v_exp_f32_e32 v15, v15
	v_exp_f32_e32 v31, v31
	v_add_f32_e32 v99, 0, v2
	v_add_f32_e32 v99, v18, v99
	v_add_f32_e32 v99, v99, v3
	v_add_f32_e32 v99, v19, v99
	v_add_f32_e32 v99, v99, v4
	v_add_f32_e32 v99, v20, v99
	v_add_f32_e32 v99, v99, v5
	v_add_f32_e32 v99, v21, v99
	v_add_f32_e32 v99, v99, v6
	v_add_f32_e32 v99, v22, v99
	v_add_f32_e32 v99, v99, v7
	v_add_f32_e32 v99, v23, v99
	v_add_f32_e32 v99, v99, v8
	v_add_f32_e32 v99, v24, v99
	v_add_f32_e32 v99, v99, v9
	v_add_f32_e32 v99, v25, v99
	v_add_f32_e32 v99, v99, v10
	v_add_f32_e32 v99, v26, v99
	v_add_f32_e32 v99, v99, v11
	v_add_f32_e32 v99, v27, v99
	v_add_f32_e32 v99, v99, v12
	v_add_f32_e32 v99, v28, v99
	v_add_f32_e32 v99, v99, v13
	v_add_f32_e32 v99, v29, v99
	v_exp_f32_e32 v16, v16
	s_waitcnt lgkmcnt(1)
	v_mfma_f32_32x32x16_bf16 v[34:49], v[100:103], v[154:157], v[34:49]
	v_add_f32_e32 v99, v99, v14
	v_exp_f32_e32 v32, v32
	v_add_f32_e32 v99, v30, v99
	v_exp_f32_e32 v17, v17
	v_add_f32_e32 v99, v99, v15
	s_waitcnt lgkmcnt(0)
	v_mfma_f32_32x32x16_bf16 v[50:65], v[104:107], v[154:157], v[50:65]
	v_exp_f32_e32 v33, v33
	v_add_f32_e32 v99, v31, v99
	v_add_f32_e32 v99, v99, v16
	v_add_f32_e32 v99, v32, v99
	v_add_f32_e32 v99, v99, v17
	v_add_f32_e32 v99, v33, v99
	v_add_u32_e32 v221, s8, v216
	v_cvt_pk_bf16_f32 v100, v2, v3
	v_cvt_pk_bf16_f32 v101, v4, v5
	v_cvt_pk_bf16_f32 v102, v6, v7
	v_cvt_pk_bf16_f32 v103, v8, v9
	v_cvt_pk_bf16_f32 v104, v10, v11
	v_cvt_pk_bf16_f32 v105, v12, v13
	v_cvt_pk_bf16_f32 v106, v14, v15
	v_cvt_pk_bf16_f32 v107, v16, v17
	v_cvt_pk_bf16_f32 v108, v18, v19
	v_cvt_pk_bf16_f32 v109, v20, v21
	v_cvt_pk_bf16_f32 v110, v22, v23
	v_cvt_pk_bf16_f32 v111, v24, v25
	v_cvt_pk_bf16_f32 v224, v26, v27
	v_cvt_pk_bf16_f32 v225, v28, v29
	v_cvt_pk_bf16_f32 v226, v30, v31
	v_cvt_pk_bf16_f32 v227, v32, v33
	s_cmp_eq_u64 s[4:5], 0
	s_cbranch_scc0 .Lstg_x_L1
	s_barrier
.Lstg_x_L1:
	ds_read_b64_tr_b16 v[112:113], v221 offset:13312
	ds_read_b64_tr_b16 v[114:115], v221 offset:13824
	ds_read_b64_tr_b16 v[116:117], v221 offset:14336
	ds_read_b64_tr_b16 v[118:119], v221 offset:14848
	s_waitcnt lgkmcnt(2)
	v_mfma_f32_32x32x16_bf16 v[82:97], v[112:115], v[100:103], v[82:97]
	ds_read_b64_tr_b16 v[112:113], v221 offset:17408
	ds_read_b64_tr_b16 v[114:115], v221 offset:17920
	ds_read_b64_tr_b16 v[120:121], v221 offset:18432
	ds_read_b64_tr_b16 v[122:123], v221 offset:18944
	v_add_f32_e32 v99, 0, v99
	v_add_f32_e32 v220, v98, v99
	s_waitcnt lgkmcnt(2)
	v_mfma_f32_32x32x16_bf16 v[66:81], v[112:115], v[100:103], v[66:81]
	s_waitcnt lgkmcnt(0)
	v_mfma_f32_32x32x16_bf16 v[66:81], v[120:123], v[104:107], v[66:81]
	ds_read_b64_tr_b16 v[98:99], v221 offset:15360
	ds_read_b64_tr_b16 v[100:101], v221 offset:15872
	ds_read_b64_tr_b16 v[112:113], v221 offset:19456
	ds_read_b64_tr_b16 v[114:115], v221 offset:19968
	v_mfma_f32_32x32x16_bf16 v[82:97], v[116:119], v[104:107], v[82:97]
	s_waitcnt lgkmcnt(0)
	v_mfma_f32_32x32x16_bf16 v[66:81], v[112:115], v[108:111], v[66:81]
	ds_read_b64_tr_b16 v[116:117], v221 offset:16384
	ds_read_b64_tr_b16 v[118:119], v221 offset:16896
	ds_read_b64_tr_b16 v[228:229], v221 offset:20480
	ds_read_b64_tr_b16 v[230:231], v221 offset:20992
	v_mfma_f32_32x32x16_bf16 v[82:97], v[98:101], v[108:111], v[82:97]
	v_max_f32_e32 v98, v51, v51
	v_max_f32_e32 v99, v50, v50
	v_max_f32_e32 v98, v99, v98
	v_max3_f32 v98, v98, v52, v53
	v_max3_f32 v98, v98, v54, v55
	v_max3_f32 v98, v98, v56, v57
	v_max3_f32 v114, v98, v58, v59
	v_max3_f32 v98, v114, v60, v61
	v_max3_f32 v99, v34, v35, v36
	s_waitcnt lgkmcnt(2)
	v_mfma_f32_32x32x16_bf16 v[82:97], v[116:119], v[224:227], v[82:97]
	v_max3_f32 v99, v99, v37, v38
	v_max3_f32 v99, v99, v39, v40
	s_waitcnt lgkmcnt(0)
	v_mfma_f32_32x32x16_bf16 v[66:81], v[228:231], v[224:227], v[66:81]
	v_max3_f32 v99, v99, v41, v42
	v_max3_f32 v99, v99, v43, v44
	v_max3_f32 v114, v99, v45, v46
	v_max3_f32 v115, v98, v62, v63
	v_max3_f32 v114, v114, v47, v48
	v_max3_f32 v115, v115, v64, v65
	v_max3_f32 v114, v114, v49, v115
	v_cmp_lt_f32_e32 vcc, 0x41000000, v114
	s_cbranch_vccz .LBB0_2993
; __device__ __forceinline__ void att_shift(float tm, bool first, float& mrun, float& lsum, fa::f32x16& o0, fa::f32x16& o1) {
;     if (first || __any(tm > mrun + 8.f)) {
;         tm = fmaxf(tm, __shfl_xor(tm, 32));
;         const float dl = first ? 0.f : fmaxf(tm - mrun, 0.f), alpha = __builtin_amdgcn_exp2f(-dl);
;         mrun = first ? tm : mrun + dl; lsum *= alpha;
; #pragma unroll
;         for (int r = 0; r < 16; ++r) { o0[r] *= alpha; o1[r] *= alpha; }
;     }
; }
; __device__ __forceinline__ void ph_attn_mfma(unsigned char* lds_, const bf16_t* Q, const bf16_t* Kb, const bf16_t* Vb, bf16_t* Z, int with_ctx, int u0, int ustep) { PH_IDS;
;     ...
;             att_shift(tmB, false, mrun, lsum, o0, o1);
;             __syncthreads();
	v_and_b32_e32 v116, 64, v1
	v_xor_b32_e32 v115, 32, v1
	v_add_u32_e32 v116, 64, v116
	v_cmp_lt_i32_e32 vcc, v115, v116
	s_nop 1
	v_cndmask_b32_e32 v115, v1, v115, vcc
	v_lshlrev_b32_e32 v115, 2, v115
	ds_bpermute_b32 v115, v115, v114
	v_max_f32_e32 v114, v114, v114
	s_waitcnt lgkmcnt(0)
	v_max_f32_e32 v115, v115, v115
	v_max_f32_e32 v114, v114, v115
	v_max_f32_e32 v115, 0, v114
	v_exp_f32_e64 v114, -v115
	v_add_f32_e32 v131, v131, v115
	v_mul_f32_e32 v220, v220, v114
	v_pk_mul_f32 v[96:97], v[96:97], v[114:115] op_sel_hi:[1,0]
	v_pk_mul_f32 v[94:95], v[94:95], v[114:115] op_sel_hi:[1,0]
	v_pk_mul_f32 v[92:93], v[92:93], v[114:115] op_sel_hi:[1,0]
	v_pk_mul_f32 v[90:91], v[90:91], v[114:115] op_sel_hi:[1,0]
	v_pk_mul_f32 v[88:89], v[88:89], v[114:115] op_sel_hi:[1,0]
	v_pk_mul_f32 v[86:87], v[86:87], v[114:115] op_sel_hi:[1,0]
	v_pk_mul_f32 v[84:85], v[84:85], v[114:115] op_sel_hi:[1,0]
	v_pk_mul_f32 v[82:83], v[82:83], v[114:115] op_sel_hi:[1,0]
	v_pk_mul_f32 v[80:81], v[80:81], v[114:115] op_sel_hi:[1,0]
	v_pk_mul_f32 v[78:79], v[78:79], v[114:115] op_sel_hi:[1,0]
	v_pk_mul_f32 v[76:77], v[76:77], v[114:115] op_sel_hi:[1,0]
	v_pk_mul_f32 v[74:75], v[74:75], v[114:115] op_sel_hi:[1,0]
	v_pk_mul_f32 v[72:73], v[72:73], v[114:115] op_sel_hi:[1,0]
	v_pk_mul_f32 v[70:71], v[70:71], v[114:115] op_sel_hi:[1,0]
	v_pk_mul_f32 v[68:69], v[68:69], v[114:115] op_sel_hi:[1,0]
	v_pk_mul_f32 v[66:67], v[66:67], v[114:115] op_sel_hi:[1,0]
	v_sub_f32_e32 v34, v34, v115
	v_sub_f32_e32 v35, v35, v115
	v_sub_f32_e32 v36, v36, v115
	v_sub_f32_e32 v37, v37, v115
	v_sub_f32_e32 v38, v38, v115
	v_sub_f32_e32 v39, v39, v115
	v_sub_f32_e32 v40, v40, v115
	v_sub_f32_e32 v41, v41, v115
	v_sub_f32_e32 v42, v42, v115
	v_sub_f32_e32 v43, v43, v115
	v_sub_f32_e32 v44, v44, v115
	v_sub_f32_e32 v45, v45, v115
	v_sub_f32_e32 v46, v46, v115
	v_sub_f32_e32 v47, v47, v115
	v_sub_f32_e32 v48, v48, v115
	v_sub_f32_e32 v49, v49, v115
	v_sub_f32_e32 v50, v50, v115
	v_sub_f32_e32 v51, v51, v115
	v_sub_f32_e32 v52, v52, v115
	v_sub_f32_e32 v53, v53, v115
	v_sub_f32_e32 v54, v54, v115
	v_sub_f32_e32 v55, v55, v115
	v_sub_f32_e32 v56, v56, v115
	v_sub_f32_e32 v57, v57, v115
	v_sub_f32_e32 v58, v58, v115
	v_sub_f32_e32 v59, v59, v115
	v_sub_f32_e32 v60, v60, v115
	v_sub_f32_e32 v61, v61, v115
	v_sub_f32_e32 v62, v62, v115
	v_sub_f32_e32 v63, v63, v115
	v_sub_f32_e32 v64, v64, v115
	v_sub_f32_e32 v65, v65, v115
	v_sub_f32_e32 v232, v232, v115
	v_sub_f32_e32 v233, v233, v115
	v_sub_f32_e32 v234, v234, v115
	v_sub_f32_e32 v235, v235, v115
	v_sub_f32_e32 v236, v236, v115
	v_sub_f32_e32 v237, v237, v115
	v_sub_f32_e32 v238, v238, v115
	v_sub_f32_e32 v239, v239, v115
	v_sub_f32_e32 v240, v240, v115
	v_sub_f32_e32 v241, v241, v115
	v_sub_f32_e32 v242, v242, v115
	v_sub_f32_e32 v243, v243, v115
	v_sub_f32_e32 v244, v244, v115
	v_sub_f32_e32 v245, v245, v115
	v_sub_f32_e32 v246, v246, v115
	v_sub_f32_e32 v247, v247, v115
.LBB0_2993:
	s_mov_b64 s[8:9], -1
	s_and_b64 vcc, exec, s[12:13]
	v_xor_b32_e32 v222, 0x80000000, v131
	s_cmp_eq_u64 s[4:5], 0
	s_cbranch_scc1 .Lstg_y_L1
	s_barrier
; __device__ __forceinline__ bf16x8 pack_p(const f32x16& p, int base) { u32x4 w; w.x = pk2(p[base], p[base + 1]); w.y = pk2(p[base + 2], p[base + 3]); w.z = pk2(p[base + 4], p[base + 5]); w.w = pk2(p[base + 6], p[base + 7]); return __builtin_bit_cast(bf16x8, w); }
; __device__ __forceinline__ float vadd1(float a, float b) { float r; asm("v_add_f32 %0, %1, %2" : "=v"(r) : "v"(a), "v"(b)); return r; }
; __device__ __forceinline__ void att_exp_pack(fa::f32x16& p0, fa::f32x16& p1, float nm, float& lsum, bf16x8 (&pf)[4]) {
;     float ps = 0.f, ps2 = 0.f;
; #pragma unroll
;     for (int r = 0; r < 16; ++r) { p0[r] = __builtin_amdgcn_exp2f(vadd1(p0[r], nm)); p1[r] = __builtin_amdgcn_exp2f(vadd1(p1[r], nm)); ps += p0[r]; ps += p1[r]; }
;     lsum += ps + ps2;
;     pf[0] = fa::pack_p(p0, 0); pf[1] = fa::pack_p(p0, 8); pf[2] = fa::pack_p(p1, 0); pf[3] = fa::pack_p(p1, 8);
; }
; __device__ __forceinline__ void ph_attn_mfma(unsigned char* lds_, const bf16_t* Q, const bf16_t* Kb, const bf16_t* Vb, bf16_t* Z, int with_ctx, int u0, int ustep) { PH_IDS;
;     ...
;                 att_exp_pack(b0, b1, -mrun, lsum, pf);
;                 pv_tile(o0, o1, sm + cur + BUF_A + vrd, pf);
.Lstg_y_L1:
	s_cbranch_vccz .LBB0_2995
	s_nop 0
	v_exp_f32_e32 v114, v34
	v_exp_f32_e32 v115, v50
	v_exp_f32_e32 v117, v35
	v_exp_f32_e32 v118, v51
	v_add_f32_e32 v116, 0, v114
	v_exp_f32_e32 v119, v36
	v_add_f32_e32 v116, v115, v116
	v_exp_f32_e32 v120, v52
	v_add_f32_e32 v116, v116, v117
	v_exp_f32_e32 v121, v37
	v_add_f32_e32 v116, v118, v116
	v_exp_f32_e32 v122, v53
	v_add_f32_e32 v116, v116, v119
	v_exp_f32_e32 v123, v38
	v_add_f32_e32 v116, v120, v116
	v_exp_f32_e32 v124, v54
	v_add_f32_e32 v116, v116, v121
	v_exp_f32_e32 v125, v39
	v_add_f32_e32 v116, v122, v116
	v_exp_f32_e32 v126, v55
	v_add_f32_e32 v116, v116, v123
	v_exp_f32_e32 v127, v40
	v_add_f32_e32 v116, v124, v116
	v_exp_f32_e32 v128, v56
	v_add_f32_e32 v116, v116, v125
	v_exp_f32_e32 v129, v41
	v_add_f32_e32 v116, v126, v116
	v_exp_f32_e32 v98, v57
	v_add_f32_e32 v116, v116, v127
	v_exp_f32_e32 v99, v42
	v_add_f32_e32 v116, v128, v116
	v_exp_f32_e32 v100, v58
	v_add_f32_e32 v116, v116, v129
	v_exp_f32_e32 v101, v43
	v_add_f32_e32 v116, v98, v116
	v_exp_f32_e32 v102, v59
	v_add_f32_e32 v116, v116, v99
	v_exp_f32_e32 v103, v44
	v_add_f32_e32 v116, v100, v116
	v_exp_f32_e32 v104, v60
	v_add_f32_e32 v116, v116, v101
	v_exp_f32_e32 v105, v45
	v_add_f32_e32 v116, v102, v116
	v_exp_f32_e32 v106, v61
	v_add_f32_e32 v116, v116, v103
	v_exp_f32_e32 v107, v46
	v_add_f32_e32 v116, v104, v116
	v_exp_f32_e32 v108, v62
	v_add_f32_e32 v116, v116, v105
	v_exp_f32_e32 v109, v47
	v_add_f32_e32 v116, v106, v116
	v_exp_f32_e32 v110, v63
	v_add_f32_e32 v116, v116, v107
	v_exp_f32_e32 v111, v48
	v_add_f32_e32 v116, v108, v116
	v_exp_f32_e32 v112, v64
	v_add_f32_e32 v116, v116, v109
	v_exp_f32_e32 v113, v49
	v_add_f32_e32 v116, v110, v116
	v_add_f32_e32 v116, v116, v111
	v_exp_f32_e32 v173, v65
	v_add_f32_e32 v116, v112, v116
	v_add_f32_e32 v116, v116, v113
	v_cvt_pk_bf16_f32 v224, v114, v117
	v_add_f32_e32 v223, v173, v116
	v_cvt_pk_bf16_f32 v225, v119, v121
	v_cvt_pk_bf16_f32 v226, v123, v125
	v_cvt_pk_bf16_f32 v227, v127, v129
	v_cvt_pk_bf16_f32 v228, v99, v101
	v_cvt_pk_bf16_f32 v229, v103, v105
	v_cvt_pk_bf16_f32 v230, v107, v109
	v_cvt_pk_bf16_f32 v231, v111, v113
	v_cvt_pk_bf16_f32 v166, v115, v118
	v_cvt_pk_bf16_f32 v167, v120, v122
	v_cvt_pk_bf16_f32 v168, v124, v126
	v_cvt_pk_bf16_f32 v169, v128, v98
	v_cvt_pk_bf16_f32 v170, v100, v102
	v_cvt_pk_bf16_f32 v171, v104, v106
	v_cvt_pk_bf16_f32 v172, v108, v110
	v_cvt_pk_bf16_f32 v173, v112, v173
	ds_read_b64_tr_b16 v[114:115], v221 offset:34816
	ds_read_b64_tr_b16 v[116:117], v221 offset:35328
	ds_read_b64_tr_b16 v[174:175], v221 offset:38912
	ds_read_b64_tr_b16 v[176:177], v221 offset:39424
	s_waitcnt lgkmcnt(2)
	v_mfma_f32_32x32x16_bf16 v[82:97], v[114:117], v[224:227], v[82:97]
	s_mov_b64 s[8:9], 0
	s_waitcnt lgkmcnt(0)
	v_mfma_f32_32x32x16_bf16 v[66:81], v[174:177], v[224:227], v[66:81]
	ds_read_b64_tr_b16 v[224:225], v221 offset:35840
	ds_read_b64_tr_b16 v[226:227], v221 offset:36352
	ds_read_b64_tr_b16 v[174:175], v221 offset:39936
	ds_read_b64_tr_b16 v[176:177], v221 offset:40448
	s_waitcnt lgkmcnt(2)
	v_mfma_f32_32x32x16_bf16 v[82:97], v[224:227], v[228:231], v[82:97]
	s_waitcnt lgkmcnt(0)
	v_mfma_f32_32x32x16_bf16 v[66:81], v[174:177], v[228:231], v[66:81]
	ds_read_b64_tr_b16 v[224:225], v221 offset:36864
	ds_read_b64_tr_b16 v[226:227], v221 offset:37376
	ds_read_b64_tr_b16 v[228:229], v221 offset:40960
	ds_read_b64_tr_b16 v[230:231], v221 offset:41472
	s_waitcnt lgkmcnt(2)
	v_mfma_f32_32x32x16_bf16 v[82:97], v[224:227], v[166:169], v[82:97]
	s_waitcnt lgkmcnt(0)
	v_mfma_f32_32x32x16_bf16 v[66:81], v[228:231], v[166:169], v[66:81]
	ds_read_b64_tr_b16 v[224:225], v221 offset:37888
	ds_read_b64_tr_b16 v[226:227], v221 offset:38400
	ds_read_b64_tr_b16 v[228:229], v221 offset:41984
	ds_read_b64_tr_b16 v[230:231], v221 offset:42496
	s_waitcnt lgkmcnt(2)
	v_mfma_f32_32x32x16_bf16 v[82:97], v[224:227], v[170:173], v[82:97]
	s_waitcnt lgkmcnt(0)
	v_mfma_f32_32x32x16_bf16 v[66:81], v[228:231], v[170:173], v[66:81]
